# v8 + mixer-B column mask folded into the QK MFMA accumulator init (per-lane masked cinit), row mask as one additive term: 48 VALU per 32-key step replaced by 16
# speedup vs baseline: 1.0094x; 1.0092x over previous
; #define LAS __attribute__((address_space(3)))
; template <int MODE, bool FIX> ...
;     ...
;         head = rem >> 4; const int r0 = 4 * (rem & 15), rp = wid >> 2, cgp = wid & 3;
;         qrow = r0 + 2 * rp + (r32 >> 4); qc = 16 * cgp + (r32 & 15); qtok = qrow * 64 + qc; qcol = 768 + head * 64; kcol = 1280 + head * 64; vcol = 1792 + head * 64; ocol = 512 + head * 64;
;         kr_lo = (r0 - 4) > 0 ? (r0 - 4) : 0; const int kr_hi = clampi(r0 - 1, 0, 56) + 7; NTL = kr_hi - kr_lo + 1; lrow0 = b * SEQ + kr_lo * 64;
;         kc0 = clampi(16 * cgp - 8, 0, 32); const int cs = clampi(qc - 8, 0, 48);
;         wa_lo = clampi(r0 + 2 * rp - 4, 0, 56); wa_hi = clampi(r0 + 2 * rp - 3, 0, 56) + 7; rs = clampi(qrow - 4, 0, 56);
; #pragma unroll
;         for (int r = 0; r < 16; ++r) { const int kc = kc0 + (r & 3) + 8 * (r >> 2) + 4 * hi; if ((unsigned)(kc - cs) < 16u) colmask |= (1u << r); }
;         LAS float* rt = (LAS float*)(lds + RPB_OFF);
;         if (tid < 465) rt[tid] = rpb[head * 465 + tid] * LOG2E;
;     }
;     ...
;     float m = FIX ? Mb : -INFINITY, l = 0.f;
;     const float ci = FIX ? -Mb : 0.f;
;     const f32x16 cinit = {ci, ci, ci, ci, ci, ci, ci, ci, ci, ci, ci, ci, ci, ci, ci, ci};
.LBB0_674:
	s_cmpk_eq_i32 s33, 0x100
	v_readlane_b32 s90, v255, 13
	s_cselect_b64 s[40:41], -1, 0
	v_readlane_b32 s1, v255, 19
	s_lshl_b32 s2, s90, 4
	s_lshl_b32 s0, s1, 2
	s_and_b32 s2, s2, 48
	s_and_b32 s0, s0, 0xffffff80
	s_and_b32 s1, s1, 31
	s_add_i32 s3, s2, -8
	v_and_b32_e32 v0, 15, v197
	s_or_b32 s0, s0, s1
	s_and_b32 s1, s85, 0x1fffffe
	s_min_u32 s3, s3, 32
	v_or_b32_e32 v149, s2, v0
	s_cmp_lg_u32 s2, 0
	v_subrev_co_u32_e32 v1, vcc, 8, v149
	s_cselect_b32 s3, s3, 0
	v_min_u32_e32 v2, 48, v1
	v_cndmask_b32_e64 v2, v2, 0, vcc
	v_add_u32_e32 v3, s3, v198
	v_sub_u32_e32 v2, v3, v2
	v_cmp_gt_u32_e32 vcc, 16, v2
	v_add_u32_e32 v4, 1, v2
	v_add_u32_e32 v5, 2, v2
	v_cndmask_b32_e64 v3, 0, 1, vcc
	v_cmp_gt_u32_e32 vcc, 16, v4
	v_add_u32_e32 v6, 3, v2
	v_add_u32_e32 v7, 8, v2
	v_cndmask_b32_e64 v4, 0, 2, vcc
	v_cmp_gt_u32_e32 vcc, 16, v5
	v_add_u32_e32 v8, 9, v2
	v_add_u32_e32 v9, 10, v2
	v_cndmask_b32_e64 v5, 0, 4, vcc
	v_cmp_gt_u32_e32 vcc, 16, v6
	v_add_u32_e32 v10, 11, v2
	v_mov_b32_e32 v11, 0x80
	v_cndmask_b32_e64 v6, 0, 8, vcc
	v_cmp_gt_u32_e32 vcc, 16, v7
	s_movk_i32 s6, 0xffef
	v_add_u32_e32 v12, 17, v2
	v_cndmask_b32_e64 v7, 0, 16, vcc
	v_cmp_gt_u32_e32 vcc, 16, v8
	v_mov_b32_e32 v13, 0x200
	v_mov_b32_e32 v14, 0x400
	v_cndmask_b32_e64 v8, 0, 32, vcc
	v_cmp_gt_u32_e32 vcc, 16, v9
	v_mov_b32_e32 v15, 0x800
	v_mov_b32_e32 v16, 0x1000
	v_cndmask_b32_e64 v9, 0, 64, vcc
	v_cmp_gt_u32_e32 vcc, 16, v10
	v_mov_b32_e32 v17, 0x2000
	v_mov_b32_e32 v18, 0x4000
	v_cndmask_b32_e32 v10, 0, v11, vcc
	v_mov_b32_e32 v11, 0x100
	v_cmp_lt_u32_e32 vcc, s6, v2
	s_add_i32 s8, 0, 0x11600
	v_readlane_b32 s95, v255, 18
	v_cndmask_b32_e32 v11, 0, v11, vcc
	v_cmp_gt_u32_e32 vcc, 16, v12
	v_or_b32_e32 v3, v11, v3
	v_or3_b32 v3, v3, v4, v5
	v_cndmask_b32_e32 v12, 0, v13, vcc
	v_add_u32_e32 v13, 18, v2
	v_cmp_gt_u32_e32 vcc, 16, v13
	v_or3_b32 v3, v3, v6, v7
	v_or3_b32 v3, v3, v8, v9
	v_cndmask_b32_e32 v13, 0, v14, vcc
	v_add_u32_e32 v14, 19, v2
	v_cmp_gt_u32_e32 vcc, 16, v14
	v_or3_b32 v3, v3, v10, v12
	v_lshl_add_u32 v151, v188, 2, s8
	v_cndmask_b32_e32 v14, 0, v15, vcc
	v_add_u32_e32 v15, 24, v2
	v_cmp_gt_u32_e32 vcc, 16, v15
	v_or3_b32 v3, v3, v13, v14
	s_lshr_b32 s8, s95, 8
	v_cndmask_b32_e32 v15, 0, v16, vcc
	v_add_u32_e32 v16, 25, v2
	v_cmp_gt_u32_e32 vcc, 16, v16
	s_mulk_i32 s8, 0xf8
	s_mov_b32 s4, 0x42400000
	v_cndmask_b32_e32 v16, 0, v17, vcc
	v_add_u32_e32 v17, 26, v2
	v_cmp_gt_u32_e32 vcc, 16, v17
	v_add_u32_e32 v2, 27, v2
	v_or3_b32 v3, v3, v15, v16
	v_cndmask_b32_e32 v17, 0, v18, vcc
	v_mov_b32_e32 v18, 0x8000
	v_cmp_gt_u32_e32 vcc, 16, v2
	s_movk_i32 s6, 0x1d1
	v_xor_b32_e32 v16, 0x80000000, v183
	v_cndmask_b32_e32 v2, 0, v18, vcc
	v_or3_b32 v150, v3, v17, v2
	v_add_u32_e32 v2, s3, v196
	v_mul_u32_u24_e32 v152, 0x90, v2
	v_or_b32_e32 v2, s3, v199
	v_lshlrev_b32_e32 v153, 6, v2
	v_sub_u32_e32 v2, s3, v0
	v_sub_u32_e32 v0, v198, v0
	v_subrev_u32_e32 v0, s2, v0
	v_subrev_u32_e32 v2, s2, v2
	v_lshlrev_b32_e32 v0, 2, v0
	v_lshl_add_u32 v2, v2, 2, v189
	v_lshl_add_u32 v0, s3, 2, v0
	v_subrev_u32_e32 v2, s8, v2
	v_subrev_u32_e32 v0, s8, v0
	v_add_u32_e32 v2, 0, v2
	v_add_u32_e32 v0, 0, v0
	v_readlane_b32 s92, v255, 9
	s_mov_b32 s43, 0
	v_cmp_ngt_f32_e64 s[4:5], s4, v183
	v_lshrrev_b32_e32 v148, 4, v196
	v_mov_b32_e32 v1, 0
	v_cmp_gt_i32_e64 s[6:7], s6, v188
	v_mov_b32_e32 v17, v16
	v_mov_b32_e32 v18, v16
	v_mov_b32_e32 v19, v16
	v_mov_b32_e32 v20, v16
	v_mov_b32_e32 v21, v16
	v_mov_b32_e32 v22, v16
	v_mov_b32_e32 v23, v16
	v_mov_b32_e32 v24, v16
	v_mov_b32_e32 v25, v16
	v_mov_b32_e32 v26, v16
	v_mov_b32_e32 v27, v16
	v_mov_b32_e32 v28, v16
	v_mov_b32_e32 v29, v16
	v_mov_b32_e32 v30, v16
	v_mov_b32_e32 v31, v16
	v_add_u32_e32 v154, 0x119a0, v2
	v_add_u32_e32 v155, 0x119a0, v0
	s_movk_i32 s2, 0x1200
	s_movk_i32 s3, 0xff84
	s_mov_b32 s46, 0xff800000
	v_mov_b32_e32 v156, 0x1200
	v_mov_b32_e32 v157, 0xff800000
	s_mov_b32 s47, 0
	v_readlane_b32 s89, v255, 14
	v_readlane_b32 s82, v255, 12
	v_readlane_b32 s83, v255, 11
	v_readlane_b32 s71, v255, 17
	v_readlane_b32 s93, v255, 10
	v_readlane_b32 s85, v255, 1
	v_readlane_b32 s56, v255, 0
	v_and_b32_e32 v212, 1, v150
	v_cmp_ne_u32_e32 vcc, 0, v212
	s_nop 1
	v_cndmask_b32_e32 v196, v157, v16, vcc
	v_and_b32_e32 v212, 2, v150
	v_cmp_ne_u32_e32 vcc, 0, v212
	s_nop 1
	v_cndmask_b32_e32 v197, v157, v17, vcc
	v_and_b32_e32 v212, 4, v150
	v_cmp_ne_u32_e32 vcc, 0, v212
	s_nop 1
	v_cndmask_b32_e32 v198, v157, v18, vcc
	v_and_b32_e32 v212, 8, v150
	v_cmp_ne_u32_e32 vcc, 0, v212
	s_nop 1
	v_cndmask_b32_e32 v199, v157, v19, vcc
	v_and_b32_e32 v212, 16, v150
	v_cmp_ne_u32_e32 vcc, 0, v212
	s_nop 1
	v_cndmask_b32_e32 v200, v157, v20, vcc
	v_and_b32_e32 v212, 32, v150
	v_cmp_ne_u32_e32 vcc, 0, v212
	s_nop 1
	v_cndmask_b32_e32 v201, v157, v21, vcc
	v_and_b32_e32 v212, 64, v150
	v_cmp_ne_u32_e32 vcc, 0, v212
	s_nop 1
	v_cndmask_b32_e32 v202, v157, v22, vcc
	v_and_b32_e32 v212, 0x80, v150
	v_cmp_ne_u32_e32 vcc, 0, v212
	s_nop 1
	v_cndmask_b32_e32 v203, v157, v23, vcc
	v_and_b32_e32 v212, 0x100, v150
	v_cmp_ne_u32_e32 vcc, 0, v212
	s_nop 1
	v_cndmask_b32_e32 v204, v157, v24, vcc
	v_and_b32_e32 v212, 0x200, v150
	v_cmp_ne_u32_e32 vcc, 0, v212
	s_nop 1
	v_cndmask_b32_e32 v205, v157, v25, vcc
	v_and_b32_e32 v212, 0x400, v150
	v_cmp_ne_u32_e32 vcc, 0, v212
	s_nop 1
	v_cndmask_b32_e32 v206, v157, v26, vcc
	v_and_b32_e32 v212, 0x800, v150
	v_cmp_ne_u32_e32 vcc, 0, v212
	s_nop 1
	v_cndmask_b32_e32 v207, v157, v27, vcc
	v_and_b32_e32 v212, 0x1000, v150
	v_cmp_ne_u32_e32 vcc, 0, v212
	s_nop 1
	v_cndmask_b32_e32 v208, v157, v28, vcc
	v_and_b32_e32 v212, 0x2000, v150
	v_cmp_ne_u32_e32 vcc, 0, v212
	s_nop 1
	v_cndmask_b32_e32 v209, v157, v29, vcc
	v_and_b32_e32 v212, 0x4000, v150
	v_cmp_ne_u32_e32 vcc, 0, v212
	s_nop 1
	v_cndmask_b32_e32 v210, v157, v30, vcc
	v_and_b32_e32 v212, 0x8000, v150
	v_cmp_ne_u32_e32 vcc, 0, v212
	s_nop 1
	v_cndmask_b32_e32 v211, v157, v31, vcc
	s_branch .LBB0_677

; template <int MASK, bool FIX> ...
;     const LAS unsigned char* kp = buf + (kvoff + r32) * KSTR + hi * 16;
;     f32x16 s = cinit;
; #pragma unroll
;     for (int d0 = 0; d0 < 4; ++d0) { const bf16x8 kf = *(const LAS bf16x8*)(kp + d0 * 32); s = __builtin_amdgcn_mfma_f32_32x32x16_bf16(kf, qf[d0], s, 0, 0, 0); }
;     const float NEG = -INFINITY;
;     if (MASK == 3) {
;         float bv[16];
; #pragma unroll
;         for (int r = 0; r < 16; ++r) bv[r] = rpbl[bidx0 + (r & 3) + 8 * (r >> 2)];
; #pragma unroll
;         for (int r = 0; r < 16; ++r) asm volatile("" : "+v"(bv[r]));
; #pragma unroll
;         for (int r = 0; r < 16; ++r) s[r] = ((vmask >> r) & 1u) ? (s[r] + bv[r]) : NEG;
;     }
; #pragma unroll
;     for (int r = 0; r < 16; ++r) {
;         const int kl0 = (r & 3) + 8 * (r >> 2);
;         if (MASK == 1) { if (kl0 + 4 * hi < r32) s[r] = NEG; }
;         if (MASK == 2) { if (kl0 + 4 * hi > r32) s[r] = NEG; }
;     }
;     if (!FIX) {
;         float mx = fmaxf(fmaxf(s[0], s[1]), fmaxf(s[2], s[3]));
; #pragma unroll
;         for (int r = 4; r < 16; r += 4) mx = fmaxf(mx, fmaxf(fmaxf(s[r], s[r + 1]), fmaxf(s[r + 2], s[r + 3])));
;         mx = swap_max(mx);
;         const float mnew = fmaxf(m, mx);
;         const float msafe = (mnew == NEG) ? 0.f : mnew;
;         if (__any(mnew > m)) {
;             const float alpha = __builtin_amdgcn_exp2f(m - msafe);
;             l *= alpha;
; #pragma unroll
;             for (int r = 0; r < 16; ++r) { o0[r] *= alpha; o1[r] *= alpha; }
;         }
;         m = mnew;
;         float ls = 0.f;
; #pragma unroll
;         for (int r = 0; r < 16; ++r) { s[r] = __builtin_amdgcn_exp2f(s[r] - msafe); ls += s[r]; }
;         l += ls;
;     } else {
; #pragma unroll
;         for (int r = 0; r < 16; ++r) s[r] = __builtin_amdgcn_exp2f(s[r]);
;         l += (((s[0] + s[1]) + (s[2] + s[3])) + ((s[4] + s[5]) + (s[6] + s[7]))) + (((s[8] + s[9]) + (s[10] + s[11])) + ((s[12] + s[13]) + (s[14] + s[15])));
;     }
;     u32x4 pw0, pw1;
;     pw0.x = cvtpk(s[0], s[1]); pw0.y = cvtpk(s[2], s[3]); pw0.z = cvtpk(s[4], s[5]); pw0.w = cvtpk(s[6], s[7]);
;     pw1.x = cvtpk(s[8], s[9]); pw1.y = cvtpk(s[10], s[11]); pw1.z = cvtpk(s[12], s[13]); pw1.w = cvtpk(s[14], s[15]);
;     const bf16x8 p0 = __builtin_bit_cast(bf16x8, pw0), p1 = __builtin_bit_cast(bf16x8, pw1);
; template <int MODE, bool FIX> ...
;     ...
;             } else {
.LBB0_727:
	s_bitcmp1_b32 s10, 0
	s_cselect_b32 s8, 0x4480, 0
	s_add_i32 s13, s48, s10
	v_add_u32_e32 v64, s10, v81
	s_add_i32 s55, s10, 1
	s_add_i32 s11, s54, s10
	s_add_i32 s14, s8, 0
	s_add_i32 s12, s13, 1
	v_cmp_gt_u32_e32 vcc, 8, v64
	v_cmp_lt_u32_e64 s[8:9], s13, v15
	s_cmp_lt_i32 s10, s49
	v_cndmask_b32_e64 v212, v157, 0, vcc
	v_cmp_gt_u32_e32 vcc, s13, v80
	s_cselect_b32 s10, s12, s11
	s_cselect_b32 s11, s51, s52
	s_and_b64 s[8:9], s[44:45], s[8:9]
	v_add_u32_e32 v65, s14, v178
	s_lshl_b32 s10, s10, 6
	s_or_b64 s[8:9], s[8:9], vcc
	v_add_u32_e32 v66, s14, v194
	s_waitcnt vmcnt(1)
	ds_write_b128 v65, v[96:99]
	s_waitcnt vmcnt(0)
	ds_write_b128 v66, v[100:103] offset:9216
	v_cndmask_b32_e64 v212, v212, v157, s[8:9]
	s_add_i32 s10, s10, s11
	v_add3_u32 v67, s14, v152, v189
	v_mad_i64_i32 v[240:241], s[8:9], s10, v156, v[104:105]
	s_nop 1
	global_load_dwordx4 v[96:99], v[240:241], off offset:2560
	global_load_dwordx4 v[100:103], v[240:241], off offset:3584
	s_waitcnt lgkmcnt(0)
	s_barrier
	ds_read_b128 v[84:87], v67
	ds_read_b128 v[88:91], v67 offset:32
	ds_read_b128 v[106:109], v67 offset:64
	ds_read_b128 v[110:113], v67 offset:96
	ds_read2_b32 v[118:119], v82 offset1:1
	ds_read2_b32 v[120:121], v82 offset0:2 offset1:3
	ds_read2_b32 v[122:123], v82 offset0:8 offset1:9
	ds_read2_b32 v[124:125], v82 offset0:10 offset1:11
	ds_read2_b32 v[126:127], v82 offset0:16 offset1:17
	ds_read2_b32 v[128:129], v82 offset0:18 offset1:19
	ds_read2_b32 v[130:131], v82 offset0:24 offset1:25
	s_waitcnt lgkmcnt(13)
	ds_read2_b32 v[132:133], v82 offset0:26 offset1:27
	v_add3_u32 v68, s14, v190, v153
	v_add3_u32 v83, v68, v191, v192
	s_waitcnt lgkmcnt(11)
	v_mfma_f32_32x32x16_bf16 v[64:79], v[84:87], v[2:5], v[196:211]
	s_waitcnt lgkmcnt(7)
	s_waitcnt lgkmcnt(6)
	s_waitcnt lgkmcnt(5)
	s_waitcnt lgkmcnt(4)
	v_mfma_f32_32x32x16_bf16 v[64:79], v[88:91], v[6:9], v[64:79]
	s_waitcnt lgkmcnt(3)
	s_waitcnt lgkmcnt(2)
	s_waitcnt lgkmcnt(1)
	v_mfma_f32_32x32x16_bf16 v[64:79], v[106:109], v[10:13], v[64:79]
	s_waitcnt lgkmcnt(0)
	ds_read_b64_tr_b16 v[84:85], v83 offset:9216
	v_mfma_f32_32x32x16_bf16 v[64:79], v[110:113], v[92:95], v[64:79]
	ds_read_b64_tr_b16 v[86:87], v83 offset:9728
	ds_read_b64_tr_b16 v[88:89], v83 offset:10240
	ds_read_b64_tr_b16 v[90:91], v83 offset:10752
	ds_read_b64_tr_b16 v[106:107], v83 offset:13376
	ds_read_b64_tr_b16 v[108:109], v83 offset:13888
	ds_read_b64_tr_b16 v[114:115], v83 offset:14400
	ds_read_b64_tr_b16 v[116:117], v83 offset:14912
	s_nop 5
	v_add_f32_e32 v213, v118, v64
	v_add_f32_e32 v214, v119, v65
	v_add_f32_e32 v215, v120, v66
	v_add_f32_e32 v216, v121, v67
	v_add_f32_e32 v217, v122, v68
	v_add_f32_e32 v218, v123, v69
	v_add_f32_e32 v219, v124, v70
	v_add_f32_e32 v220, v125, v71
	v_add_f32_e32 v221, v126, v72
	v_add_f32_e32 v222, v127, v73
	v_add_f32_e32 v223, v128, v74
	v_add_f32_e32 v224, v129, v75
	v_add_f32_e32 v225, v130, v76
	v_add_f32_e32 v226, v131, v77
	v_add_f32_e32 v227, v132, v78
	v_add_f32_e32 v228, v133, v79
	v_add_f32_e32 v213, v212, v213
	v_add_f32_e32 v214, v212, v214
	v_add_f32_e32 v215, v212, v215
	v_add_f32_e32 v216, v212, v216
	v_add_f32_e32 v217, v212, v217
	v_add_f32_e32 v218, v212, v218
	v_add_f32_e32 v219, v212, v219
	v_add_f32_e32 v220, v212, v220
	v_add_f32_e32 v221, v212, v221
	v_add_f32_e32 v222, v212, v222
	v_add_f32_e32 v223, v212, v223
	v_add_f32_e32 v224, v212, v224
	v_add_f32_e32 v225, v212, v225
	v_add_f32_e32 v226, v212, v226
	v_add_f32_e32 v227, v212, v227
	v_add_f32_e32 v228, v212, v228
	v_exp_f32_e32 v68, v213
	v_exp_f32_e32 v70, v214
	v_exp_f32_e32 v72, v215
	v_exp_f32_e32 v74, v216
	v_exp_f32_e32 v76, v217
	v_exp_f32_e32 v78, v218
	v_exp_f32_e32 v110, v219
	v_exp_f32_e32 v112, v220
	v_cvt_pk_bf16_f32 v64, v68, v70
	v_cvt_pk_bf16_f32 v65, v72, v74
	v_cvt_pk_bf16_f32 v66, v76, v78
	v_cvt_pk_bf16_f32 v67, v110, v112
	s_nop 0
	s_waitcnt lgkmcnt(6)
	v_mfma_f32_32x32x16_bf16 v[32:47], v[84:87], v[64:67], v[32:47]
	s_waitcnt lgkmcnt(2)
	v_mfma_f32_32x32x16_bf16 v[48:63], v[106:109], v[64:67], v[48:63]
	v_exp_f32_e32 v69, v221
	v_exp_f32_e32 v71, v222
	v_exp_f32_e32 v73, v223
	v_exp_f32_e32 v75, v224
	v_exp_f32_e32 v77, v225
	v_exp_f32_e32 v79, v226
	v_exp_f32_e32 v111, v227
	v_exp_f32_e32 v113, v228
	v_cvt_pk_bf16_f32 v64, v69, v71
	v_cvt_pk_bf16_f32 v65, v73, v75
	v_cvt_pk_bf16_f32 v66, v77, v79
	v_cvt_pk_bf16_f32 v67, v111, v113
	v_pk_add_f32 v[68:69], v[68:69], v[70:71]
	v_pk_add_f32 v[70:71], v[72:73], v[74:75]
	v_mfma_f32_32x32x16_bf16 v[32:47], v[88:91], v[64:67], v[32:47]
	v_add_f32_e64 v68, v68, v70
	v_add_f32_e64 v69, v69, v71
	s_mov_b32 s10, s55
	v_add_u32_e32 v82, 0x7c, v82
	s_cmp_eq_u32 s42, s55
	s_waitcnt lgkmcnt(0)
	v_mfma_f32_32x32x16_bf16 v[48:63], v[114:117], v[64:67], v[48:63]
	v_add_f32_e64 v64, v76, v78
	v_add_f32_e64 v65, v77, v79
	v_add_f32_e64 v66, v110, v112
	v_add_f32_e64 v67, v111, v113
	v_add_f32_e64 v64, v64, v66
	v_add_f32_e64 v65, v65, v67
	v_pk_add_f32 v[64:65], v[68:69], v[64:65]
	s_nop 0
	v_add_f32_e32 v64, v64, v65
	v_add_f32_e32 v0, v0, v64
	s_cbranch_scc0 .LBB0_727
	s_add_i32 s11, s49, 1
	s_branch .LBB0_730
